# sparse work split: K/V block load charged 1.0 tile instead of 0.5 (v75 otherwise)
# baseline (speedup 1.0000x reference)
.LBB0_789:
	s_or_b64 exec, exec, s[4:5]
	v_and_b32_e32 v1, 63, v0
	s_cmp_lt_u32 s33, 64
	v_and_b32_e32 v7, 64, v6
	v_cmp_gt_u32_e32 vcc, 32, v1
	s_waitcnt lgkmcnt(0)
	s_barrier
	s_cbranch_scc0 .LBB0_793
	v_lshlrev_b32_e32 v20, 6, v1
	v_add_u32_e32 v2, 0, v20
	v_add_u32_e32 v16, 0x20400, v2
	ds_read_b128 v[2:5], v16
	s_movk_i32 s6, 0xff
	ds_read_b128 v[8:11], v16 offset:16
	ds_read_b128 v[12:15], v16 offset:32
	ds_read_b128 v[16:19], v16 offset:48
	v_add_u32_e32 v38, -2, v6
	s_add_i32 s16, 0, 0x21400
	s_waitcnt lgkmcnt(3)
	v_add_u32_e32 v2, 0xff, v2
	v_add_u32_e32 v3, 0xff, v3
	v_lshrrev_b32_e32 v24, 8, v2
	v_lshl_add_u32 v24, v24, 3, 8
	v_lshrrev_b32_e32 v23, 8, v3
	v_lshl_add_u32 v23, v23, 3, 8
	v_cmp_lt_u32_e64 s[4:5], s6, v2
	v_lshrrev_b32_e32 v21, 8, v2
	v_cndmask_b32_e64 v24, 0, v24, s[4:5]
	v_cmp_lt_u32_e64 s[4:5], s6, v3
	v_lshrrev_b32_e32 v22, 8, v3
	s_waitcnt lgkmcnt(2)
	v_add_u32_e32 v8, 0xff, v8
	v_cndmask_b32_e64 v2, 0, v23, s[4:5]
	v_add_u32_e32 v23, v2, v24
	v_add_u32_e32 v2, 0xff, v4
	v_lshrrev_b32_e32 v4, 8, v2
	v_lshl_add_u32 v4, v4, 3, 8
	v_cmp_lt_u32_e64 s[4:5], s6, v2
	v_lshrrev_b32_e32 v3, 8, v2
	v_lshrrev_b32_e32 v26, 8, v8
	v_lshl_add_u32 v26, v26, 3, 8
	v_cndmask_b32_e64 v2, 0, v4, s[4:5]
	v_add_u32_e32 v4, 0xff, v5
	v_lshrrev_b32_e32 v25, 8, v4
	v_lshl_add_u32 v25, v25, 3, 8
	v_cmp_lt_u32_e64 s[4:5], s6, v4
	v_add_u32_e32 v9, 0xff, v9
	v_lshrrev_b32_e32 v5, 8, v4
	v_cndmask_b32_e64 v4, 0, v25, s[4:5]
	v_cmp_lt_u32_e64 s[4:5], s6, v8
	v_lshrrev_b32_e32 v27, 8, v9
	v_lshl_add_u32 v27, v27, 3, 8
	v_add_u32_e32 v10, 0xff, v10
	v_add_u32_e32 v22, v22, v21
	v_lshrrev_b32_e32 v25, 8, v8
	v_cndmask_b32_e64 v8, 0, v26, s[4:5]
	v_cmp_lt_u32_e64 s[4:5], s6, v9
	v_lshrrev_b32_e32 v28, 8, v10
	v_lshl_add_u32 v28, v28, 3, 8
	v_add_u32_e32 v11, 0xff, v11
	v_lshrrev_b32_e32 v26, 8, v9
	v_cndmask_b32_e64 v9, 0, v27, s[4:5]
	v_cmp_lt_u32_e64 s[4:5], s6, v10
	v_lshrrev_b32_e32 v29, 8, v11
	v_lshl_add_u32 v29, v29, 3, 8
	s_waitcnt lgkmcnt(1)
	v_add_u32_e32 v12, 0xff, v12
	v_add_u32_e32 v3, v3, v22
	v_lshrrev_b32_e32 v27, 8, v10
	v_cndmask_b32_e64 v10, 0, v28, s[4:5]
	v_cmp_lt_u32_e64 s[4:5], s6, v11
	v_lshrrev_b32_e32 v30, 8, v12
	v_lshl_add_u32 v30, v30, 3, 8
	v_add_u32_e32 v13, 0xff, v13
	v_add_u32_e32 v5, v5, v3
	v_lshrrev_b32_e32 v28, 8, v11
	v_cndmask_b32_e64 v11, 0, v29, s[4:5]
	v_cmp_lt_u32_e64 s[4:5], s6, v12
	v_lshrrev_b32_e32 v31, 8, v13
	v_lshl_add_u32 v31, v31, 3, 8
	v_add_u32_e32 v14, 0xff, v14
	v_add_u32_e32 v25, v25, v5
	v_lshrrev_b32_e32 v29, 8, v12
	v_cndmask_b32_e64 v12, 0, v30, s[4:5]
	v_cmp_lt_u32_e64 s[4:5], s6, v13
	v_lshrrev_b32_e32 v32, 8, v14
	v_lshl_add_u32 v32, v32, 3, 8
	v_add_u32_e32 v15, 0xff, v15
	v_add_u32_e32 v26, v26, v25
	v_lshrrev_b32_e32 v30, 8, v13
	v_cndmask_b32_e64 v13, 0, v31, s[4:5]
	v_cmp_lt_u32_e64 s[4:5], s6, v14
	v_lshrrev_b32_e32 v33, 8, v15
	v_lshl_add_u32 v33, v33, 3, 8
	s_waitcnt lgkmcnt(0)
	v_add_u32_e32 v16, 0xff, v16
	v_add_u32_e32 v27, v27, v26
	v_lshrrev_b32_e32 v31, 8, v14
	v_cndmask_b32_e64 v14, 0, v32, s[4:5]
	v_cmp_lt_u32_e64 s[4:5], s6, v15
	v_lshrrev_b32_e32 v34, 8, v16
	v_lshl_add_u32 v34, v34, 3, 8
	v_add_u32_e32 v17, 0xff, v17
	v_add_u32_e32 v28, v28, v27
	v_lshrrev_b32_e32 v32, 8, v15
	v_cndmask_b32_e64 v15, 0, v33, s[4:5]
	v_cmp_lt_u32_e64 s[4:5], s6, v16
	v_lshrrev_b32_e32 v35, 8, v17
	v_lshl_add_u32 v35, v35, 3, 8
	v_add_u32_e32 v18, 0xff, v18
	v_add_u32_e32 v29, v29, v28
	v_lshrrev_b32_e32 v33, 8, v16
	v_cndmask_b32_e64 v16, 0, v34, s[4:5]
	v_cmp_lt_u32_e64 s[4:5], s6, v17
	v_lshrrev_b32_e32 v36, 8, v18
	v_lshl_add_u32 v36, v36, 3, 8
	v_add_u32_e32 v19, 0xff, v19
	v_add_u32_e32 v30, v30, v29
	v_lshrrev_b32_e32 v34, 8, v17
	v_cndmask_b32_e64 v17, 0, v35, s[4:5]
	v_cmp_lt_u32_e64 s[4:5], s6, v18
	v_lshrrev_b32_e32 v37, 8, v19
	v_lshl_add_u32 v37, v37, 3, 8
	v_add_u32_e32 v31, v31, v30
	v_lshrrev_b32_e32 v35, 8, v18
	v_cndmask_b32_e64 v18, 0, v36, s[4:5]
	v_cmp_lt_u32_e64 s[4:5], s6, v19
	v_add_u32_e32 v32, v32, v31
	v_lshrrev_b32_e32 v36, 8, v19
	v_cndmask_b32_e64 v19, 0, v37, s[4:5]
	v_add_u32_e32 v37, -1, v6
	v_add_u32_e32 v33, v33, v32
	v_cmp_lt_i32_e64 s[4:5], v37, v7
	v_add_u32_e32 v47, v2, v23
	v_add_u32_e32 v34, v34, v33
	v_cndmask_b32_e64 v37, v37, v6, s[4:5]
	s_add_i32 s17, 0, 0x22800
	v_add_u32_e32 v4, v4, v47
	v_or_b32_e32 v2, 20, v20
	v_add_u32_e32 v35, v35, v34
	v_lshlrev_b32_e32 v37, 2, v37
	v_cmp_lt_i32_e64 s[4:5], v38, v7
	v_add_u32_e32 v39, -4, v6
	v_add_u32_e32 v48, s16, v2
	v_add_u32_e32 v49, s17, v2
	v_add_u32_e32 v50, v8, v4
	v_or_b32_e32 v2, 28, v20
	v_add_u32_e32 v8, v36, v35
	v_cndmask_b32_e64 v38, v38, v6, s[4:5]
	v_cmp_lt_i32_e64 s[4:5], v39, v7
	v_add_u32_e32 v40, -8, v6
	v_add_u32_e32 v52, s16, v2
	v_add_u32_e32 v53, s17, v2
	ds_bpermute_b32 v2, v37, v8
	v_cndmask_b32_e64 v39, v39, v6, s[4:5]
	v_cmp_lt_i32_e64 s[4:5], v40, v7
	v_add_u32_e32 v41, -16, v6
	v_subrev_u32_e32 v42, 32, v6
	v_cndmask_b32_e64 v40, v40, v6, s[4:5]
	v_cmp_lt_i32_e64 s[4:5], v41, v7
	v_lshlrev_b32_e32 v38, 2, v38
	v_add_u32_e32 v51, v9, v50
	v_cndmask_b32_e64 v41, v41, v6, s[4:5]
	v_cmp_lt_i32_e64 s[4:5], v42, v7
	v_add_u32_e32 v36, v10, v51
	v_or_b32_e32 v9, 36, v20
	v_cndmask_b32_e64 v42, v42, v6, s[4:5]
	v_cmp_eq_u32_e64 s[4:5], 0, v1
	v_cmp_gt_u32_e64 s[6:7], 2, v1
	v_add_u32_e32 v54, v11, v36
	s_waitcnt lgkmcnt(0)
	v_cndmask_b32_e64 v2, v2, 0, s[4:5]
	v_add_u32_e32 v2, v8, v2
	ds_bpermute_b32 v10, v38, v2
	v_add_u32_e32 v11, s16, v9
	v_add_u32_e32 v55, s17, v9
	v_lshlrev_b32_e32 v39, 2, v39
	v_cmp_gt_u32_e64 s[8:9], 4, v1
	s_waitcnt lgkmcnt(0)
	v_cndmask_b32_e64 v9, v10, 0, s[6:7]
	v_add_u32_e32 v2, v2, v9
	ds_bpermute_b32 v9, v39, v2
	v_lshlrev_b32_e32 v40, 2, v40
	v_cmp_gt_u32_e64 s[10:11], 8, v1
	v_lshlrev_b32_e32 v41, 2, v41
	v_add_u32_e32 v56, v12, v54
	s_waitcnt lgkmcnt(0)
	v_cndmask_b32_e64 v9, v9, 0, s[8:9]
	v_add_u32_e32 v2, v9, v2
	ds_bpermute_b32 v9, v40, v2
	v_add_u32_e32 v13, v13, v56
	v_add_u32_e32 v14, v14, v13
	v_add_u32_e32 v15, v15, v14
	v_cmp_gt_u32_e64 s[12:13], 16, v1
	s_waitcnt lgkmcnt(0)
	v_cndmask_b32_e64 v9, v9, 0, s[10:11]
	v_add_u32_e32 v2, v9, v2
	ds_bpermute_b32 v9, v41, v2
	v_add_u32_e32 v16, v16, v15
	v_lshlrev_b32_e32 v42, 2, v42
	v_add_u32_e32 v17, v17, v16
	v_add_u32_e32 v18, v18, v17
	s_waitcnt lgkmcnt(0)
	v_cndmask_b32_e64 v9, v9, 0, s[12:13]
	v_add_u32_e32 v2, v9, v2
	ds_bpermute_b32 v9, v42, v2
	v_add_u32_e32 v19, v19, v18
	ds_bpermute_b32 v37, v37, v19
	v_or_b32_e32 v10, 44, v20
	v_add_u32_e32 v12, s16, v10
	s_waitcnt lgkmcnt(1)
	v_cndmask_b32_e64 v9, v9, 0, vcc
	v_add_u32_e32 v2, v9, v2
	v_add_u32_e32 v57, s17, v10
	v_or_b32_e32 v10, 52, v20
	v_sub_u32_e32 v8, v2, v8
	s_waitcnt lgkmcnt(0)
	v_cndmask_b32_e64 v9, v37, 0, s[4:5]
	v_add_u32_e32 v58, s16, v10
	v_add_u32_e32 v59, s17, v10
	v_add_u32_e32 v10, v8, v22
	v_add_u32_e32 v22, v19, v9
	ds_bpermute_b32 v37, v38, v22
	v_add_u32_e32 v43, s16, v20
	v_add_u32_e32 v9, v8, v21
	ds_write_b96 v43, v[8:10]
	v_or_b32_e32 v45, 12, v20
	s_waitcnt lgkmcnt(1)
	v_cndmask_b32_e64 v9, v37, 0, s[6:7]
	v_add_u32_e32 v9, v22, v9
	ds_bpermute_b32 v10, v39, v9
	v_add_u32_e32 v46, s16, v45
	v_add_u32_e32 v5, v8, v5
	v_add_u32_e32 v3, v8, v3
	ds_write2_b32 v46, v3, v5 offset1:1
	v_add_u32_e32 v3, v8, v26
	v_add_u32_e32 v5, v8, v25
	ds_write2_b32 v48, v5, v3 offset1:1
	s_waitcnt lgkmcnt(2)
	v_cndmask_b32_e64 v3, v10, 0, s[8:9]
	v_add_u32_e32 v3, v9, v3
	ds_bpermute_b32 v5, v40, v3
	v_add_u32_e32 v9, v8, v28
	v_add_u32_e32 v10, v8, v27
	ds_write2_b32 v52, v10, v9 offset1:1
	v_add_u32_e32 v9, v8, v30
	s_waitcnt lgkmcnt(1)
	v_cndmask_b32_e64 v5, v5, 0, s[10:11]
	v_add_u32_e32 v3, v3, v5
	ds_bpermute_b32 v5, v41, v3
	v_add_u32_e32 v10, v8, v29
	ds_write2_b32 v11, v10, v9 offset1:1
	v_add_u32_e32 v9, v8, v32
	v_add_u32_e32 v10, v8, v31
	s_waitcnt lgkmcnt(1)
	v_cndmask_b32_e64 v5, v5, 0, s[12:13]
	v_add_u32_e32 v3, v5, v3
	ds_bpermute_b32 v5, v42, v3
	ds_write2_b32 v12, v10, v9 offset1:1
	v_add_u32_e32 v9, v8, v34
	v_add_u32_e32 v10, v8, v33
	ds_write2_b32 v58, v10, v9 offset1:1
	s_waitcnt lgkmcnt(2)
	v_cndmask_b32_e64 v5, v5, 0, vcc
	v_add_u32_e32 v3, v5, v3
	v_sub_u32_e32 v10, v3, v19
	v_add_u32_e32 v45, s17, v45
	v_add_u32_e32 v4, v10, v4
	v_add_u32_e32 v5, v10, v47
	ds_write2_b32 v45, v5, v4 offset1:1
	v_add_u32_e32 v4, v10, v51
	v_add_u32_e32 v5, v10, v50
	ds_write2_b32 v49, v5, v4 offset1:1
	v_add_u32_e32 v4, v10, v54
	v_add_u32_e32 v5, v10, v36
	ds_write2_b32 v53, v5, v4 offset1:1
	v_add_u32_e32 v4, v10, v13
	v_add_u32_e32 v5, v10, v56
	ds_write2_b32 v55, v5, v4 offset1:1
	v_add_u32_e32 v4, v10, v15
	v_add_u32_e32 v5, v10, v14
	ds_write2_b32 v57, v5, v4 offset1:1
	v_add_u32_e32 v4, v10, v17
	v_add_u32_e32 v5, v10, v16
	ds_write2_b32 v59, v5, v4 offset1:1
	v_or_b32_e32 v5, 60, v20
	v_add_u32_e32 v4, v8, v35
	v_add_u32_e32 v8, s16, v5
	v_add_u32_e32 v44, s17, v20
	v_add_u32_e32 v12, v10, v23
	v_add_u32_e32 v11, v10, v24
	ds_write_b32 v8, v4
	v_add_u32_e32 v4, v10, v18
	v_add_u32_e32 v5, s17, v5
	v_cmp_eq_u32_e32 vcc, 63, v1
	ds_write_b96 v44, v[10:12]
	ds_write_b32 v5, v4
	s_and_saveexec_b64 s[4:5], vcc
	s_cbranch_execz .LBB0_792
	s_add_i32 s6, 0, 0x22400
	v_mov_b32_e32 v4, s6
	s_add_i32 s6, 0, 0x23800
	ds_write_b32 v4, v2
	v_mov_b32_e32 v2, s6
	ds_write_b32 v2, v3

.LBB0_798:
	s_add_i32 s7, s5, s4
	s_ashr_i32 s7, s7, 1
	s_lshl_b32 s10, s7, 2
	s_add_i32 s10, s10, 0
	s_add_i32 s10, s10, 0x22800
	v_mov_b32_e32 v4, s10
	ds_read_b32 v4, v4
	s_waitcnt lgkmcnt(0)
	v_readfirstlane_b32 s10, v4
	s_cmp_gt_u32 s10, s6
	s_cselect_b32 s5, s7, s5
	s_cselect_b32 s4, s4, s7
	s_sub_i32 s7, s5, s4
	s_cmp_gt_i32 s7, 1
	s_cbranch_scc1 .LBB0_798
	s_lshl_b32 s4, s4, 2
	s_add_i32 s4, s4, 0
	s_add_i32 s5, s4, 0x21400
	s_add_i32 s4, s4, 0x22800
	v_mov_b32_e32 v4, s5
	v_mov_b32_e32 v8, s4
	ds_read2_b32 v[4:5], v4 offset1:1
	ds_read_b32 v8, v8
	s_waitcnt lgkmcnt(1)
	v_readfirstlane_b32 s4, v4
	s_waitcnt lgkmcnt(0)
	v_readfirstlane_b32 s10, v8
	v_readfirstlane_b32 s5, v5
	s_add_i32 s11, s10, 8
	s_sub_i32 s10, s6, s10
	s_sub_i32 s7, s5, s4
	s_add_i32 s10, s10, -1
	s_lshr_b32 s10, s10, 3
	s_cmp_lt_u32 s11, s6
	s_cselect_b32 s6, s10, 0
	s_add_i32 s4, s6, s4
	s_cmp_lt_u32 s6, s7
	s_cselect_b32 s66, s4, s5

.LBB0_805:
	s_add_i32 s7, s5, s4
	s_ashr_i32 s7, s7, 1
	s_lshl_b32 s8, s7, 2
	s_add_i32 s8, s8, 0
	s_add_i32 s8, s8, 0x22800
	v_mov_b32_e32 v2, s8
	ds_read_b32 v2, v2
	s_waitcnt lgkmcnt(0)
	v_readfirstlane_b32 s8, v2
	s_cmp_gt_u32 s8, s6
	s_cselect_b32 s5, s7, s5
	s_cselect_b32 s4, s4, s7
	s_sub_i32 s7, s5, s4
	s_cmp_gt_i32 s7, 1
	s_cbranch_scc1 .LBB0_805
	s_lshl_b32 s4, s4, 2
	s_add_i32 s4, s4, 0
	s_add_i32 s5, s4, 0x21400
	s_add_i32 s4, s4, 0x22800
	v_mov_b32_e32 v2, s5
	v_mov_b32_e32 v4, s4
	ds_read2_b32 v[2:3], v2 offset1:1
	ds_read_b32 v4, v4
	s_waitcnt lgkmcnt(1)
	v_sub_u32_e32 v5, v3, v2
	s_waitcnt lgkmcnt(0)
	v_add_u32_e32 v8, 8, v4
	v_sub_u32_e32 v4, s6, v4
	v_add_u32_e32 v4, -1, v4
	v_lshrrev_b32_e32 v4, 3, v4
	v_cmp_gt_u32_e32 vcc, s6, v8
	s_nop 1
	v_cndmask_b32_e32 v4, 0, v4, vcc
	v_add_u32_e32 v2, v4, v2
	v_cmp_lt_u32_e32 vcc, v4, v5
	s_nop 1
	v_cndmask_b32_e32 v186, v3, v2, vcc
